# v177 plus P4 epilogue with coalesced x loads and h1b stores through the per-wave LDS tile
# speedup vs baseline: 1.0129x; 1.0129x over previous
; __device__ __forceinline__ u32x4 pack8(const float (&f)[8]) { u32x4 w; w.x = cvt_pk_bf16(f[0], f[1]); w.y = cvt_pk_bf16(f[2], f[3]); w.z = cvt_pk_bf16(f[4], f[5]); w.w = cvt_pk_bf16(f[6], f[7]); return w; }
;     __device__ __forceinline__ void operator()(const f32x4 (&acc)[2][2][4][2], const Unit& u, int wr, int wc, int fr, int fq) const {
;         const int row0 = u.pm * BM + wr * 64 + fr, col0 = u.pn * BM + wc * 32 + 8 * fq;
; #pragma unroll
;         for (int ai = 0; ai < 2; ++ai)
; #pragma unroll
;             for (int m = 0; m < 4; ++m) { const int row = row0 + ai * HALF + m * 16; const size_t idx = (size_t)row * 1024 + col0; float ss = 0.f;
; #pragma unroll
;                 for (int bj = 0; bj < 2; ++bj) { const f32x4 x0 = __builtin_nontemporal_load((const f32x4*)(x + idx + bj * HALF)), x1 = __builtin_nontemporal_load((const f32x4*)(x + idx + bj * HALF + 4));
;                     const f32x4 h0 = x0 + acc[ai][bj][m][0], h1v = x1 + acc[ai][bj][m][1];
;                     float f[8] = {h0[0], h0[1], h0[2], h0[3], h1v[0], h1v[1], h1v[2], h1v[3]};
; #pragma unroll
;                     for (int e = 0; e < 8; ++e) ss += f[e] * f[e];
;                     *(u32x4*)(h1b + idx + bj * HALF) = pack8(f); }
;                 ss += __shfl_xor(ss, 16); ss += __shfl_xor(ss, 32);
;                 if (fq == 0) atomicAdd(ssq + row, ss); }
.LBB0_648:
	v_lshl_add_u32 v148, s44, 8, v150
	v_lshlrev_b32_e32 v149, 2, v148
	v_bfe_u32 v236, v150, 6, 1
	v_bfe_u32 v237, v152, 5, 2
	v_lshl_or_b32 v236, v236, 2, v237
	v_mul_u32_u24_e32 v236, 0x500, v236
	v_add_u32_e32 v236, 0x20000, v236
	v_and_b32_e32 v237, 7, v150
	v_bfe_u32 v238, v152, 3, 2
	v_lshlrev_b32_e32 v238, 1, v238
	v_xor_b32_e32 v239, v238, v237
	v_lshlrev_b32_e32 v239, 4, v239
	v_lshl_add_u32 v227, v237, 7, v239
	v_add_u32_e32 v227, v227, v236
	v_or_b32_e32 v238, 1, v238
	v_xor_b32_e32 v239, v238, v237
	v_lshlrev_b32_e32 v239, 4, v239
	v_lshl_add_u32 v228, v237, 7, v239
	v_add_u32_e32 v228, v228, v236
	v_lshrrev_b32_e32 v237, 3, v156
	v_and_b32_e32 v238, 7, v156
	v_xor_b32_e32 v239, v238, v237
	v_lshlrev_b32_e32 v239, 4, v239
	v_lshl_add_u32 v226, v237, 7, v239
	v_add_u32_e32 v226, v226, v236
	v_and_or_b32 v147, v150, -16, v237
	v_lshl_add_u32 v147, s44, 8, v147
	v_and_b32_e32 v239, 0xffffffe7, v152
	v_lshl_or_b32 v239, s46, 8, v239
	v_lshl_add_u32 v239, v238, 2, v239
	v_lshl_add_u32 v147, v147, 10, v239
	v_lshlrev_b32_e32 v147, 2, v147
	v_add_u32_e32 v144, 0x8000, v147
	v_and_b32_e32 v237, 15, v150
	v_mul_u32_u24_e32 v234, 0x50, v237
	v_bfe_u32 v238, v152, 3, 2
	v_lshl_add_u32 v234, v238, 4, v234
	v_add_u32_e32 v234, v234, v236
	v_lshrrev_b32_e32 v237, 2, v156
	v_and_b32_e32 v238, 3, v156
	v_mul_u32_u24_e32 v235, 0x50, v237
	v_lshl_add_u32 v235, v238, 4, v235
	v_add_u32_e32 v235, v235, v236
	v_and_or_b32 v145, v150, -16, v237
	v_lshl_add_u32 v145, s44, 8, v145
	v_and_b32_e32 v239, 0xffffffe7, v152
	v_lshl_or_b32 v239, s46, 8, v239
	v_lshl_add_u32 v239, v238, 3, v239
	v_lshl_add_u32 v145, v145, 10, v239
	v_lshlrev_b32_e32 v145, 1, v145
	s_mov_b32 s98, 0x00ff00ff
	s_mov_b32 s99, 0x00ff00ff
	s_mov_b32 s100, 0xff00ff00
	s_mov_b32 s101, 0xff00ff00
	global_load_dwordx4 v[158:161], v147, s[52:53] nt
	global_load_dwordx4 v[162:165], v144, s[52:53] nt
	global_load_dwordx4 v[166:169], v147, s[52:53] offset:512 nt
	global_load_dwordx4 v[170:173], v144, s[52:53] offset:512 nt
	v_add_u32_e32 v147, 0x10000, v147
	v_add_u32_e32 v144, 0x10000, v144
	global_load_dwordx4 v[174:177], v147, s[52:53] nt
	global_load_dwordx4 v[178:181], v144, s[52:53] nt
	global_load_dwordx4 v[182:185], v147, s[52:53] offset:512 nt
	global_load_dwordx4 v[186:189], v144, s[52:53] offset:512 nt
	v_add_u32_e32 v147, 0x10000, v147
	v_add_u32_e32 v144, 0x10000, v144
	global_load_dwordx4 v[190:193], v147, s[52:53] nt
	global_load_dwordx4 v[194:197], v144, s[52:53] nt
	global_load_dwordx4 v[198:201], v147, s[52:53] offset:512 nt
	global_load_dwordx4 v[206:209], v144, s[52:53] offset:512 nt
	v_add_u32_e32 v147, 0x10000, v147
	v_add_u32_e32 v144, 0x10000, v144
	global_load_dwordx4 v[210:213], v147, s[52:53] nt
	global_load_dwordx4 v[214:217], v144, s[52:53] nt
	global_load_dwordx4 v[218:221], v147, s[52:53] offset:512 nt
	global_load_dwordx4 v[222:225], v144, s[52:53] offset:512 nt
	v_add_u32_e32 v147, 0x50000, v147
	v_add_u32_e32 v144, 0x50000, v144
	s_waitcnt vmcnt(12)
	ds_write_b128 v226, v[158:161]
	s_mov_b64 exec, s[98:99]
	ds_read_b128 v[158:161], v227
	ds_read_b128 v[230:233], v228
	s_mov_b64 exec, -1
	ds_write_b128 v226, v[162:165]
	s_mov_b64 exec, s[100:101]
	ds_read_b128 v[158:161], v227
	ds_read_b128 v[230:233], v228
	s_mov_b64 exec, -1
	s_waitcnt lgkmcnt(0)
	v_pk_add_f32 v[124:125], v[124:125], v[158:159]
	v_pk_add_f32 v[126:127], v[126:127], v[160:161]
	v_pk_add_f32 v[120:121], v[120:121], v[230:231]
	v_pk_add_f32 v[122:123], v[122:123], v[232:233]
	ds_write_b128 v226, v[166:169]
	s_mov_b64 exec, s[98:99]
	ds_read_b128 v[166:169], v227
	ds_read_b128 v[230:233], v228
	s_mov_b64 exec, -1
	ds_write_b128 v226, v[170:173]
	s_mov_b64 exec, s[100:101]
	ds_read_b128 v[166:169], v227
	ds_read_b128 v[230:233], v228
	s_mov_b64 exec, -1
	s_waitcnt lgkmcnt(0)
	v_pk_add_f32 v[116:117], v[116:117], v[166:167]
	v_pk_add_f32 v[118:119], v[118:119], v[168:169]
	v_pk_add_f32 v[112:113], v[112:113], v[230:231]
	v_pk_add_f32 v[114:115], v[114:115], v[232:233]
	v_cvt_pk_bf16_f32 v158, v124, v125
	v_cvt_pk_bf16_f32 v159, v126, v127
	v_cvt_pk_bf16_f32 v160, v120, v121
	v_cvt_pk_bf16_f32 v161, v122, v123
	v_cvt_pk_bf16_f32 v166, v116, v117
	v_cvt_pk_bf16_f32 v167, v118, v119
	v_cvt_pk_bf16_f32 v168, v112, v113
	v_cvt_pk_bf16_f32 v169, v114, v115
	ds_write_b128 v234, v[158:161]
	ds_read_b128 v[158:161], v235
	ds_write_b128 v234, v[166:169]
	ds_read_b128 v[166:169], v235
	v_mul_f32_e32 v157, v124, v124
	v_fmac_f32_e32 v157, v125, v125
	v_fmac_f32_e32 v157, v126, v126
	v_fmac_f32_e32 v157, v127, v127
	v_fmac_f32_e32 v157, v120, v120
	v_fmac_f32_e32 v157, v121, v121
	v_fmac_f32_e32 v157, v122, v122
	v_fmac_f32_e32 v157, v123, v123
	v_fmac_f32_e32 v157, v116, v116
	v_fmac_f32_e32 v157, v117, v117
	v_fmac_f32_e32 v157, v118, v118
	v_fmac_f32_e32 v157, v119, v119
	v_fmac_f32_e32 v157, v112, v112
	v_fmac_f32_e32 v157, v113, v113
	v_fmac_f32_e32 v157, v114, v114
	v_fmac_f32_e32 v157, v115, v115
	s_waitcnt lgkmcnt(2)
	global_store_dwordx4 v145, v[158:161], s[8:9]
	s_waitcnt lgkmcnt(0)
	global_store_dwordx4 v145, v[166:169], s[8:9] offset:256
	v_add_u32_e32 v145, 0x8000, v145
	global_load_dwordx4 v[158:161], v147, s[52:53] nt
	global_load_dwordx4 v[162:165], v144, s[52:53] nt
	global_load_dwordx4 v[166:169], v147, s[52:53] offset:512 nt
	global_load_dwordx4 v[170:173], v144, s[52:53] offset:512 nt
	v_add_u32_e32 v147, 0x10000, v147
	v_add_u32_e32 v144, 0x10000, v144
	s_waitcnt vmcnt(14)
	ds_write_b128 v226, v[174:177]
	s_mov_b64 exec, s[98:99]
	ds_read_b128 v[174:177], v227
	ds_read_b128 v[230:233], v228
	s_mov_b64 exec, -1
	ds_write_b128 v226, v[178:181]
	s_mov_b64 exec, s[100:101]
	ds_read_b128 v[174:177], v227
	ds_read_b128 v[230:233], v228
	s_mov_b64 exec, -1
	s_waitcnt lgkmcnt(0)
; __device__ __forceinline__ u32x4 pack8(const float (&f)[8]) { u32x4 w; w.x = cvt_pk_bf16(f[0], f[1]); w.y = cvt_pk_bf16(f[2], f[3]); w.z = cvt_pk_bf16(f[4], f[5]); w.w = cvt_pk_bf16(f[6], f[7]); return w; }
;     __device__ __forceinline__ void operator()(const f32x4 (&acc)[2][2][4][2], const Unit& u, int wr, int wc, int fr, int fq) const {
;         const int row0 = u.pm * BM + wr * 64 + fr, col0 = u.pn * BM + wc * 32 + 8 * fq;
; #pragma unroll
;         for (int ai = 0; ai < 2; ++ai)
; #pragma unroll
;             for (int m = 0; m < 4; ++m) { const int row = row0 + ai * HALF + m * 16; const size_t idx = (size_t)row * 1024 + col0; float ss = 0.f;
; #pragma unroll
;                 for (int bj = 0; bj < 2; ++bj) { const f32x4 x0 = __builtin_nontemporal_load((const f32x4*)(x + idx + bj * HALF)), x1 = __builtin_nontemporal_load((const f32x4*)(x + idx + bj * HALF + 4));
;                     const f32x4 h0 = x0 + acc[ai][bj][m][0], h1v = x1 + acc[ai][bj][m][1];
;                     float f[8] = {h0[0], h0[1], h0[2], h0[3], h1v[0], h1v[1], h1v[2], h1v[3]};
; #pragma unroll
;                     for (int e = 0; e < 8; ++e) ss += f[e] * f[e];
;                     *(u32x4*)(h1b + idx + bj * HALF) = pack8(f); }
;                 ss += __shfl_xor(ss, 16); ss += __shfl_xor(ss, 32);
;                 if (fq == 0) atomicAdd(ssq + row, ss); }
	v_pk_add_f32 v[108:109], v[108:109], v[174:175]
	v_pk_add_f32 v[110:111], v[110:111], v[176:177]
	v_pk_add_f32 v[104:105], v[104:105], v[230:231]
	v_pk_add_f32 v[106:107], v[106:107], v[232:233]
	ds_write_b128 v226, v[182:185]
	s_mov_b64 exec, s[98:99]
	ds_read_b128 v[182:185], v227
	ds_read_b128 v[230:233], v228
	s_mov_b64 exec, -1
	ds_write_b128 v226, v[186:189]
	s_mov_b64 exec, s[100:101]
	ds_read_b128 v[182:185], v227
	ds_read_b128 v[230:233], v228
	s_mov_b64 exec, -1
	s_waitcnt lgkmcnt(0)
	v_pk_add_f32 v[100:101], v[100:101], v[182:183]
	v_pk_add_f32 v[102:103], v[102:103], v[184:185]
	v_pk_add_f32 v[96:97], v[96:97], v[230:231]
	v_pk_add_f32 v[98:99], v[98:99], v[232:233]
	v_cvt_pk_bf16_f32 v174, v108, v109
	v_cvt_pk_bf16_f32 v175, v110, v111
	v_cvt_pk_bf16_f32 v176, v104, v105
	v_cvt_pk_bf16_f32 v177, v106, v107
	v_cvt_pk_bf16_f32 v182, v100, v101
	v_cvt_pk_bf16_f32 v183, v102, v103
	v_cvt_pk_bf16_f32 v184, v96, v97
	v_cvt_pk_bf16_f32 v185, v98, v99
	ds_write_b128 v234, v[174:177]
	ds_read_b128 v[174:177], v235
	ds_write_b128 v234, v[182:185]
	ds_read_b128 v[182:185], v235
	v_mul_f32_e32 v202, v108, v108
	v_fmac_f32_e32 v202, v109, v109
	v_fmac_f32_e32 v202, v110, v110
	v_fmac_f32_e32 v202, v111, v111
	v_fmac_f32_e32 v202, v104, v104
	v_fmac_f32_e32 v202, v105, v105
	v_fmac_f32_e32 v202, v106, v106
	v_fmac_f32_e32 v202, v107, v107
	v_fmac_f32_e32 v202, v100, v100
	v_fmac_f32_e32 v202, v101, v101
	v_fmac_f32_e32 v202, v102, v102
	v_fmac_f32_e32 v202, v103, v103
	v_fmac_f32_e32 v202, v96, v96
	v_fmac_f32_e32 v202, v97, v97
	v_fmac_f32_e32 v202, v98, v98
	v_fmac_f32_e32 v202, v99, v99
	s_waitcnt lgkmcnt(2)
	global_store_dwordx4 v145, v[174:177], s[8:9]
	s_waitcnt lgkmcnt(0)
	global_store_dwordx4 v145, v[182:185], s[8:9] offset:256
	v_add_u32_e32 v145, 0x8000, v145
	global_load_dwordx4 v[174:177], v147, s[52:53] nt
	global_load_dwordx4 v[178:181], v144, s[52:53] nt
	global_load_dwordx4 v[182:185], v147, s[52:53] offset:512 nt
	global_load_dwordx4 v[186:189], v144, s[52:53] offset:512 nt
	v_add_u32_e32 v147, 0x10000, v147
	v_add_u32_e32 v144, 0x10000, v144
	s_waitcnt vmcnt(16)
	ds_write_b128 v226, v[190:193]
	s_mov_b64 exec, s[98:99]
	ds_read_b128 v[190:193], v227
	ds_read_b128 v[230:233], v228
	s_mov_b64 exec, -1
	ds_write_b128 v226, v[194:197]
	s_mov_b64 exec, s[100:101]
	ds_read_b128 v[190:193], v227
	ds_read_b128 v[230:233], v228
	s_mov_b64 exec, -1
	s_waitcnt lgkmcnt(0)
	v_pk_add_f32 v[92:93], v[92:93], v[190:191]
	v_pk_add_f32 v[94:95], v[94:95], v[192:193]
	v_pk_add_f32 v[88:89], v[88:89], v[230:231]
	v_pk_add_f32 v[90:91], v[90:91], v[232:233]
	ds_write_b128 v226, v[198:201]
	s_mov_b64 exec, s[98:99]
	ds_read_b128 v[198:201], v227
	ds_read_b128 v[230:233], v228
	s_mov_b64 exec, -1
	ds_write_b128 v226, v[206:209]
	s_mov_b64 exec, s[100:101]
	ds_read_b128 v[198:201], v227
	ds_read_b128 v[230:233], v228
	s_mov_b64 exec, -1
	s_waitcnt lgkmcnt(0)
	v_pk_add_f32 v[84:85], v[84:85], v[198:199]
	v_pk_add_f32 v[86:87], v[86:87], v[200:201]
	v_pk_add_f32 v[80:81], v[80:81], v[230:231]
	v_pk_add_f32 v[82:83], v[82:83], v[232:233]
	v_cvt_pk_bf16_f32 v190, v92, v93
	v_cvt_pk_bf16_f32 v191, v94, v95
	v_cvt_pk_bf16_f32 v192, v88, v89
	v_cvt_pk_bf16_f32 v193, v90, v91
	v_cvt_pk_bf16_f32 v198, v84, v85
	v_cvt_pk_bf16_f32 v199, v86, v87
	v_cvt_pk_bf16_f32 v200, v80, v81
	v_cvt_pk_bf16_f32 v201, v82, v83
	ds_write_b128 v234, v[190:193]
	ds_read_b128 v[190:193], v235
	ds_write_b128 v234, v[198:201]
	ds_read_b128 v[198:201], v235
	v_mul_f32_e32 v203, v92, v92
	v_fmac_f32_e32 v203, v93, v93
	v_fmac_f32_e32 v203, v94, v94
	v_fmac_f32_e32 v203, v95, v95
	v_fmac_f32_e32 v203, v88, v88
	v_fmac_f32_e32 v203, v89, v89
	v_fmac_f32_e32 v203, v90, v90
	v_fmac_f32_e32 v203, v91, v91
	v_fmac_f32_e32 v203, v84, v84
	v_fmac_f32_e32 v203, v85, v85
	v_fmac_f32_e32 v203, v86, v86
	v_fmac_f32_e32 v203, v87, v87
	v_fmac_f32_e32 v203, v80, v80
	v_fmac_f32_e32 v203, v81, v81
	v_fmac_f32_e32 v203, v82, v82
	v_fmac_f32_e32 v203, v83, v83
	s_waitcnt lgkmcnt(2)
	global_store_dwordx4 v145, v[190:193], s[8:9]
	s_waitcnt lgkmcnt(0)
	global_store_dwordx4 v145, v[198:201], s[8:9] offset:256
	v_add_u32_e32 v145, 0x8000, v145
	global_load_dwordx4 v[190:193], v147, s[52:53] nt
	global_load_dwordx4 v[194:197], v144, s[52:53] nt
	global_load_dwordx4 v[198:201], v147, s[52:53] offset:512 nt
	global_load_dwordx4 v[206:209], v144, s[52:53] offset:512 nt
	v_add_u32_e32 v147, 0x10000, v147
	v_add_u32_e32 v144, 0x10000, v144
	s_waitcnt vmcnt(18)
	ds_write_b128 v226, v[210:213]
	s_mov_b64 exec, s[98:99]
	ds_read_b128 v[210:213], v227
	ds_read_b128 v[230:233], v228
	s_mov_b64 exec, -1
	ds_write_b128 v226, v[214:217]
	s_mov_b64 exec, s[100:101]
	ds_read_b128 v[210:213], v227
	ds_read_b128 v[230:233], v228
	s_mov_b64 exec, -1
	s_waitcnt lgkmcnt(0)
	v_pk_add_f32 v[76:77], v[76:77], v[210:211]
	v_pk_add_f32 v[78:79], v[78:79], v[212:213]
	v_pk_add_f32 v[72:73], v[72:73], v[230:231]
	v_pk_add_f32 v[74:75], v[74:75], v[232:233]
	ds_write_b128 v226, v[218:221]
	s_mov_b64 exec, s[98:99]
	ds_read_b128 v[218:221], v227
	ds_read_b128 v[230:233], v228
	s_mov_b64 exec, -1
	ds_write_b128 v226, v[222:225]
	s_mov_b64 exec, s[100:101]
	ds_read_b128 v[218:221], v227
	ds_read_b128 v[230:233], v228
	s_mov_b64 exec, -1
	s_waitcnt lgkmcnt(0)
; __device__ __forceinline__ u32x4 pack8(const float (&f)[8]) { u32x4 w; w.x = cvt_pk_bf16(f[0], f[1]); w.y = cvt_pk_bf16(f[2], f[3]); w.z = cvt_pk_bf16(f[4], f[5]); w.w = cvt_pk_bf16(f[6], f[7]); return w; }
;     __device__ __forceinline__ void operator()(const f32x4 (&acc)[2][2][4][2], const Unit& u, int wr, int wc, int fr, int fq) const {
;         const int row0 = u.pm * BM + wr * 64 + fr, col0 = u.pn * BM + wc * 32 + 8 * fq;
; #pragma unroll
;         for (int ai = 0; ai < 2; ++ai)
; #pragma unroll
;             for (int m = 0; m < 4; ++m) { const int row = row0 + ai * HALF + m * 16; const size_t idx = (size_t)row * 1024 + col0; float ss = 0.f;
; #pragma unroll
;                 for (int bj = 0; bj < 2; ++bj) { const f32x4 x0 = __builtin_nontemporal_load((const f32x4*)(x + idx + bj * HALF)), x1 = __builtin_nontemporal_load((const f32x4*)(x + idx + bj * HALF + 4));
;                     const f32x4 h0 = x0 + acc[ai][bj][m][0], h1v = x1 + acc[ai][bj][m][1];
;                     float f[8] = {h0[0], h0[1], h0[2], h0[3], h1v[0], h1v[1], h1v[2], h1v[3]};
; #pragma unroll
;                     for (int e = 0; e < 8; ++e) ss += f[e] * f[e];
;                     *(u32x4*)(h1b + idx + bj * HALF) = pack8(f); }
;                 ss += __shfl_xor(ss, 16); ss += __shfl_xor(ss, 32);
;                 if (fq == 0) atomicAdd(ssq + row, ss); }
	v_pk_add_f32 v[68:69], v[68:69], v[218:219]
	v_pk_add_f32 v[70:71], v[70:71], v[220:221]
	v_pk_add_f32 v[64:65], v[64:65], v[230:231]
	v_pk_add_f32 v[66:67], v[66:67], v[232:233]
	v_cvt_pk_bf16_f32 v210, v76, v77
	v_cvt_pk_bf16_f32 v211, v78, v79
	v_cvt_pk_bf16_f32 v212, v72, v73
	v_cvt_pk_bf16_f32 v213, v74, v75
	v_cvt_pk_bf16_f32 v218, v68, v69
	v_cvt_pk_bf16_f32 v219, v70, v71
	v_cvt_pk_bf16_f32 v220, v64, v65
	v_cvt_pk_bf16_f32 v221, v66, v67
	ds_write_b128 v234, v[210:213]
	ds_read_b128 v[210:213], v235
	ds_write_b128 v234, v[218:221]
	ds_read_b128 v[218:221], v235
	v_mul_f32_e32 v205, v76, v76
	v_fmac_f32_e32 v205, v77, v77
	v_fmac_f32_e32 v205, v78, v78
	v_fmac_f32_e32 v205, v79, v79
	v_fmac_f32_e32 v205, v72, v72
	v_fmac_f32_e32 v205, v73, v73
	v_fmac_f32_e32 v205, v74, v74
	v_fmac_f32_e32 v205, v75, v75
	v_fmac_f32_e32 v205, v68, v68
	v_fmac_f32_e32 v205, v69, v69
	v_fmac_f32_e32 v205, v70, v70
	v_fmac_f32_e32 v205, v71, v71
	v_fmac_f32_e32 v205, v64, v64
	v_fmac_f32_e32 v205, v65, v65
	v_fmac_f32_e32 v205, v66, v66
	v_fmac_f32_e32 v205, v67, v67
	s_waitcnt lgkmcnt(2)
	global_store_dwordx4 v145, v[210:213], s[8:9]
	s_waitcnt lgkmcnt(0)
	global_store_dwordx4 v145, v[218:221], s[8:9] offset:256
	v_add_u32_e32 v145, 0x28000, v145
	global_load_dwordx4 v[210:213], v147, s[52:53] nt
	global_load_dwordx4 v[214:217], v144, s[52:53] nt
	global_load_dwordx4 v[218:221], v147, s[52:53] offset:512 nt
	global_load_dwordx4 v[222:225], v144, s[52:53] offset:512 nt
	s_waitcnt vmcnt(18)
	ds_write_b128 v226, v[158:161]
	s_mov_b64 exec, s[98:99]
	ds_read_b128 v[158:161], v227
	ds_read_b128 v[230:233], v228
	s_mov_b64 exec, -1
	ds_write_b128 v226, v[162:165]
	s_mov_b64 exec, s[100:101]
	ds_read_b128 v[158:161], v227
	ds_read_b128 v[230:233], v228
	s_mov_b64 exec, -1
	s_waitcnt lgkmcnt(0)
	v_pk_add_f32 v[60:61], v[60:61], v[158:159]
	v_pk_add_f32 v[62:63], v[62:63], v[160:161]
	v_pk_add_f32 v[56:57], v[56:57], v[230:231]
	v_pk_add_f32 v[58:59], v[58:59], v[232:233]
	ds_write_b128 v226, v[166:169]
	s_mov_b64 exec, s[98:99]
	ds_read_b128 v[166:169], v227
	ds_read_b128 v[230:233], v228
	s_mov_b64 exec, -1
	ds_write_b128 v226, v[170:173]
	s_mov_b64 exec, s[100:101]
	ds_read_b128 v[166:169], v227
	ds_read_b128 v[230:233], v228
	s_mov_b64 exec, -1
	s_waitcnt lgkmcnt(0)
	v_pk_add_f32 v[52:53], v[52:53], v[166:167]
	v_pk_add_f32 v[54:55], v[54:55], v[168:169]
	v_pk_add_f32 v[48:49], v[48:49], v[230:231]
	v_pk_add_f32 v[50:51], v[50:51], v[232:233]
	v_cvt_pk_bf16_f32 v158, v60, v61
	v_cvt_pk_bf16_f32 v159, v62, v63
	v_cvt_pk_bf16_f32 v160, v56, v57
	v_cvt_pk_bf16_f32 v161, v58, v59
	v_cvt_pk_bf16_f32 v166, v52, v53
	v_cvt_pk_bf16_f32 v167, v54, v55
	v_cvt_pk_bf16_f32 v168, v48, v49
	v_cvt_pk_bf16_f32 v169, v50, v51
	ds_write_b128 v234, v[158:161]
	ds_read_b128 v[158:161], v235
	ds_write_b128 v234, v[166:169]
	ds_read_b128 v[166:169], v235
	v_mul_f32_e32 v242, v60, v60
	v_fmac_f32_e32 v242, v61, v61
	v_fmac_f32_e32 v242, v62, v62
	v_fmac_f32_e32 v242, v63, v63
	v_fmac_f32_e32 v242, v56, v56
	v_fmac_f32_e32 v242, v57, v57
	v_fmac_f32_e32 v242, v58, v58
	v_fmac_f32_e32 v242, v59, v59
	v_fmac_f32_e32 v242, v52, v52
	v_fmac_f32_e32 v242, v53, v53
	v_fmac_f32_e32 v242, v54, v54
	v_fmac_f32_e32 v242, v55, v55
	v_fmac_f32_e32 v242, v48, v48
	v_fmac_f32_e32 v242, v49, v49
	v_fmac_f32_e32 v242, v50, v50
	v_fmac_f32_e32 v242, v51, v51
	s_waitcnt lgkmcnt(2)
	global_store_dwordx4 v145, v[158:161], s[8:9]
	s_waitcnt lgkmcnt(0)
	global_store_dwordx4 v145, v[166:169], s[8:9] offset:256
	v_add_u32_e32 v145, 0x8000, v145
	s_waitcnt vmcnt(14)
	ds_write_b128 v226, v[174:177]
	s_mov_b64 exec, s[98:99]
	ds_read_b128 v[174:177], v227
	ds_read_b128 v[230:233], v228
	s_mov_b64 exec, -1
	ds_write_b128 v226, v[178:181]
	s_mov_b64 exec, s[100:101]
	ds_read_b128 v[174:177], v227
	ds_read_b128 v[230:233], v228
	s_mov_b64 exec, -1
	s_waitcnt lgkmcnt(0)
	v_pk_add_f32 v[44:45], v[44:45], v[174:175]
	v_pk_add_f32 v[46:47], v[46:47], v[176:177]
	v_pk_add_f32 v[40:41], v[40:41], v[230:231]
	v_pk_add_f32 v[42:43], v[42:43], v[232:233]
	ds_write_b128 v226, v[182:185]
	s_mov_b64 exec, s[98:99]
	ds_read_b128 v[182:185], v227
	ds_read_b128 v[230:233], v228
	s_mov_b64 exec, -1
	ds_write_b128 v226, v[186:189]
	s_mov_b64 exec, s[100:101]
	ds_read_b128 v[182:185], v227
	ds_read_b128 v[230:233], v228
	s_mov_b64 exec, -1
	s_waitcnt lgkmcnt(0)
	v_pk_add_f32 v[36:37], v[36:37], v[182:183]
	v_pk_add_f32 v[38:39], v[38:39], v[184:185]
	v_pk_add_f32 v[32:33], v[32:33], v[230:231]
	v_pk_add_f32 v[34:35], v[34:35], v[232:233]
	v_cvt_pk_bf16_f32 v174, v44, v45
	v_cvt_pk_bf16_f32 v175, v46, v47
	v_cvt_pk_bf16_f32 v176, v40, v41
	v_cvt_pk_bf16_f32 v177, v42, v43
	v_cvt_pk_bf16_f32 v182, v36, v37
	v_cvt_pk_bf16_f32 v183, v38, v39
	v_cvt_pk_bf16_f32 v184, v32, v33
	v_cvt_pk_bf16_f32 v185, v34, v35
	ds_write_b128 v234, v[174:177]
	ds_read_b128 v[174:177], v235
	ds_write_b128 v234, v[182:185]
	ds_read_b128 v[182:185], v235
	v_mul_f32_e32 v243, v44, v44
	v_fmac_f32_e32 v243, v45, v45
	v_fmac_f32_e32 v243, v46, v46
	v_fmac_f32_e32 v243, v47, v47
	v_fmac_f32_e32 v243, v40, v40
	v_fmac_f32_e32 v243, v41, v41
	v_fmac_f32_e32 v243, v42, v42
	v_fmac_f32_e32 v243, v43, v43
	v_fmac_f32_e32 v243, v36, v36
	v_fmac_f32_e32 v243, v37, v37
	v_fmac_f32_e32 v243, v38, v38
	v_fmac_f32_e32 v243, v39, v39
	v_fmac_f32_e32 v243, v32, v32
	v_fmac_f32_e32 v243, v33, v33
	v_fmac_f32_e32 v243, v34, v34
	v_fmac_f32_e32 v243, v35, v35
	s_waitcnt lgkmcnt(2)
	global_store_dwordx4 v145, v[174:177], s[8:9]
	s_waitcnt lgkmcnt(0)
	global_store_dwordx4 v145, v[182:185], s[8:9] offset:256
	v_add_u32_e32 v145, 0x8000, v145
	s_waitcnt vmcnt(10)
; __device__ __forceinline__ u32x4 pack8(const float (&f)[8]) { u32x4 w; w.x = cvt_pk_bf16(f[0], f[1]); w.y = cvt_pk_bf16(f[2], f[3]); w.z = cvt_pk_bf16(f[4], f[5]); w.w = cvt_pk_bf16(f[6], f[7]); return w; }
;     __device__ __forceinline__ void operator()(const f32x4 (&acc)[2][2][4][2], const Unit& u, int wr, int wc, int fr, int fq) const {
;         const int row0 = u.pm * BM + wr * 64 + fr, col0 = u.pn * BM + wc * 32 + 8 * fq;
; #pragma unroll
;         for (int ai = 0; ai < 2; ++ai)
; #pragma unroll
;             for (int m = 0; m < 4; ++m) { const int row = row0 + ai * HALF + m * 16; const size_t idx = (size_t)row * 1024 + col0; float ss = 0.f;
; #pragma unroll
;                 for (int bj = 0; bj < 2; ++bj) { const f32x4 x0 = __builtin_nontemporal_load((const f32x4*)(x + idx + bj * HALF)), x1 = __builtin_nontemporal_load((const f32x4*)(x + idx + bj * HALF + 4));
;                     const f32x4 h0 = x0 + acc[ai][bj][m][0], h1v = x1 + acc[ai][bj][m][1];
;                     float f[8] = {h0[0], h0[1], h0[2], h0[3], h1v[0], h1v[1], h1v[2], h1v[3]};
; #pragma unroll
;                     for (int e = 0; e < 8; ++e) ss += f[e] * f[e];
;                     *(u32x4*)(h1b + idx + bj * HALF) = pack8(f); }
;                 ss += __shfl_xor(ss, 16); ss += __shfl_xor(ss, 32);
;                 if (fq == 0) atomicAdd(ssq + row, ss); }
	ds_write_b128 v226, v[190:193]
	s_mov_b64 exec, s[98:99]
	ds_read_b128 v[190:193], v227
	ds_read_b128 v[230:233], v228
	s_mov_b64 exec, -1
	ds_write_b128 v226, v[194:197]
	s_mov_b64 exec, s[100:101]
	ds_read_b128 v[190:193], v227
	ds_read_b128 v[230:233], v228
	s_mov_b64 exec, -1
	s_waitcnt lgkmcnt(0)
	v_pk_add_f32 v[28:29], v[28:29], v[190:191]
	v_pk_add_f32 v[30:31], v[30:31], v[192:193]
	v_pk_add_f32 v[24:25], v[24:25], v[230:231]
	v_pk_add_f32 v[26:27], v[26:27], v[232:233]
	ds_write_b128 v226, v[198:201]
	s_mov_b64 exec, s[98:99]
	ds_read_b128 v[198:201], v227
	ds_read_b128 v[230:233], v228
	s_mov_b64 exec, -1
	ds_write_b128 v226, v[206:209]
	s_mov_b64 exec, s[100:101]
	ds_read_b128 v[198:201], v227
	ds_read_b128 v[230:233], v228
	s_mov_b64 exec, -1
	s_waitcnt lgkmcnt(0)
	v_pk_add_f32 v[20:21], v[20:21], v[198:199]
	v_pk_add_f32 v[22:23], v[22:23], v[200:201]
	v_pk_add_f32 v[16:17], v[16:17], v[230:231]
	v_pk_add_f32 v[18:19], v[18:19], v[232:233]
	v_cvt_pk_bf16_f32 v190, v28, v29
	v_cvt_pk_bf16_f32 v191, v30, v31
	v_cvt_pk_bf16_f32 v192, v24, v25
	v_cvt_pk_bf16_f32 v193, v26, v27
	v_cvt_pk_bf16_f32 v198, v20, v21
	v_cvt_pk_bf16_f32 v199, v22, v23
	v_cvt_pk_bf16_f32 v200, v16, v17
	v_cvt_pk_bf16_f32 v201, v18, v19
	ds_write_b128 v234, v[190:193]
	ds_read_b128 v[190:193], v235
	ds_write_b128 v234, v[198:201]
	ds_read_b128 v[198:201], v235
	v_mul_f32_e32 v244, v28, v28
	v_fmac_f32_e32 v244, v29, v29
	v_fmac_f32_e32 v244, v30, v30
	v_fmac_f32_e32 v244, v31, v31
	v_fmac_f32_e32 v244, v24, v24
	v_fmac_f32_e32 v244, v25, v25
	v_fmac_f32_e32 v244, v26, v26
	v_fmac_f32_e32 v244, v27, v27
	v_fmac_f32_e32 v244, v20, v20
	v_fmac_f32_e32 v244, v21, v21
	v_fmac_f32_e32 v244, v22, v22
	v_fmac_f32_e32 v244, v23, v23
	v_fmac_f32_e32 v244, v16, v16
	v_fmac_f32_e32 v244, v17, v17
	v_fmac_f32_e32 v244, v18, v18
	v_fmac_f32_e32 v244, v19, v19
	s_waitcnt lgkmcnt(2)
	global_store_dwordx4 v145, v[190:193], s[8:9]
	s_waitcnt lgkmcnt(0)
	global_store_dwordx4 v145, v[198:201], s[8:9] offset:256
	v_add_u32_e32 v145, 0x8000, v145
	s_waitcnt vmcnt(6)
	ds_write_b128 v226, v[210:213]
	s_mov_b64 exec, s[98:99]
	ds_read_b128 v[210:213], v227
	ds_read_b128 v[230:233], v228
	s_mov_b64 exec, -1
	ds_write_b128 v226, v[214:217]
	s_mov_b64 exec, s[100:101]
	ds_read_b128 v[210:213], v227
	ds_read_b128 v[230:233], v228
	s_mov_b64 exec, -1
	s_waitcnt lgkmcnt(0)
	v_pk_add_f32 v[12:13], v[12:13], v[210:211]
	v_pk_add_f32 v[14:15], v[14:15], v[212:213]
	v_pk_add_f32 v[8:9], v[8:9], v[230:231]
	v_pk_add_f32 v[10:11], v[10:11], v[232:233]
	ds_write_b128 v226, v[218:221]
	s_mov_b64 exec, s[98:99]
	ds_read_b128 v[218:221], v227
	ds_read_b128 v[230:233], v228
	s_mov_b64 exec, -1
	ds_write_b128 v226, v[222:225]
	s_mov_b64 exec, s[100:101]
	ds_read_b128 v[218:221], v227
	ds_read_b128 v[230:233], v228
	s_mov_b64 exec, -1
	s_waitcnt lgkmcnt(0)
	v_pk_add_f32 v[4:5], v[4:5], v[218:219]
	v_pk_add_f32 v[6:7], v[6:7], v[220:221]
	v_pk_add_f32 v[0:1], v[0:1], v[230:231]
	v_pk_add_f32 v[2:3], v[2:3], v[232:233]
	v_cvt_pk_bf16_f32 v210, v12, v13
	v_cvt_pk_bf16_f32 v211, v14, v15
	v_cvt_pk_bf16_f32 v212, v8, v9
	v_cvt_pk_bf16_f32 v213, v10, v11
	v_cvt_pk_bf16_f32 v218, v4, v5
	v_cvt_pk_bf16_f32 v219, v6, v7
	v_cvt_pk_bf16_f32 v220, v0, v1
	v_cvt_pk_bf16_f32 v221, v2, v3
	ds_write_b128 v234, v[210:213]
	ds_read_b128 v[210:213], v235
	ds_write_b128 v234, v[218:221]
	ds_read_b128 v[218:221], v235
	v_mul_f32_e32 v245, v12, v12
	v_fmac_f32_e32 v245, v13, v13
	v_fmac_f32_e32 v245, v14, v14
	v_fmac_f32_e32 v245, v15, v15
	v_fmac_f32_e32 v245, v8, v8
	v_fmac_f32_e32 v245, v9, v9
	v_fmac_f32_e32 v245, v10, v10
	v_fmac_f32_e32 v245, v11, v11
	v_fmac_f32_e32 v245, v4, v4
	v_fmac_f32_e32 v245, v5, v5
	v_fmac_f32_e32 v245, v6, v6
	v_fmac_f32_e32 v245, v7, v7
	v_fmac_f32_e32 v245, v0, v0
	v_fmac_f32_e32 v245, v1, v1
	v_fmac_f32_e32 v245, v2, v2
	v_fmac_f32_e32 v245, v3, v3
	s_waitcnt lgkmcnt(2)
	global_store_dwordx4 v145, v[210:213], s[8:9]
	s_waitcnt lgkmcnt(0)
	global_store_dwordx4 v145, v[218:221], s[8:9] offset:256
	v_xor_b32_e32 v158, 16, v156
	v_xor_b32_e32 v159, 32, v156
	v_lshlrev_b32_e32 v158, 2, v158
	v_lshlrev_b32_e32 v159, 2, v159
	ds_bpermute_b32 v162, v158, v157
	ds_bpermute_b32 v163, v158, v202
	ds_bpermute_b32 v164, v158, v203
	ds_bpermute_b32 v165, v158, v205
	ds_bpermute_b32 v166, v158, v242
	ds_bpermute_b32 v167, v158, v243
	ds_bpermute_b32 v168, v158, v244
	ds_bpermute_b32 v169, v158, v245
	s_waitcnt lgkmcnt(0)
	v_add_f32_e32 v157, v157, v162
	v_add_f32_e32 v202, v202, v163
	v_add_f32_e32 v203, v203, v164
	v_add_f32_e32 v205, v205, v165
	v_add_f32_e32 v242, v242, v166
	v_add_f32_e32 v243, v243, v167
	v_add_f32_e32 v244, v244, v168
	v_add_f32_e32 v245, v245, v169
	ds_bpermute_b32 v162, v159, v157
	ds_bpermute_b32 v163, v159, v202
	ds_bpermute_b32 v164, v159, v203
	ds_bpermute_b32 v165, v159, v205
	ds_bpermute_b32 v166, v159, v242
	ds_bpermute_b32 v167, v159, v243
	ds_bpermute_b32 v168, v159, v244
	ds_bpermute_b32 v169, v159, v245
	s_waitcnt lgkmcnt(0)
	v_add_f32_e32 v157, v157, v162
	v_add_f32_e32 v202, v202, v163
	v_add_f32_e32 v203, v203, v164
	v_add_f32_e32 v205, v205, v165
	v_add_f32_e32 v242, v242, v166
	v_add_f32_e32 v243, v243, v167
	v_add_f32_e32 v244, v244, v168
	v_add_f32_e32 v245, v245, v169
	s_and_saveexec_b64 s[44:45], s[4:5]
	global_atomic_add_f32 v149, v157, s[68:69]
	global_atomic_add_f32 v149, v202, s[68:69] offset:64
	global_atomic_add_f32 v149, v203, s[68:69] offset:128
	global_atomic_add_f32 v149, v205, s[68:69] offset:192
	global_atomic_add_f32 v149, v242, s[68:69] offset:512
	global_atomic_add_f32 v149, v243, s[68:69] offset:576
	global_atomic_add_f32 v149, v244, s[68:69] offset:640
	global_atomic_add_f32 v149, v245, s[68:69] offset:704
	s_or_b64 exec, exec, s[44:45]
	s_andn2_b64 vcc, exec, s[6:7]
	s_mov_b64 s[6:7], -1
	s_cbranch_vccnz .LBB0_637
	s_andn2_b64 vcc, exec, s[12:13]
	s_cbranch_vccnz .LBB0_636
	s_barrier
	s_branch .LBB0_636
